# hand-written QK loop of the sample memory attention: K rows prefetched one iteration ahead, 8 interleaved dot2 chains, DPP stages interleaved
# speedup vs baseline: 1.0100x; 1.0100x over previous
; __device__ __forceinline__ void memattn_unit(const Ctx& C, int r0, const float* kp0, const float* vp0, unsigned char* lds, int lane) {
;     ...
;     const bf16_t* qmem = (const bf16_t*)(C.ws + WS_QMEM); const float* ssq = (const float*)(C.ws + ACC_SSQ);
;     {
;         unsigned q[8][8]; float rsq[8];
; #pragma unroll
;         for (int qi = 0; qi < 8; ++qi) { const u32x4 a = *(const u32x4*)(qmem + (size_t)(r0 + qi) * 1024 + lane * 16), bq = *(const u32x4*)(qmem + (size_t)(r0 + qi) * 1024 + lane * 16 + 8);
;             q[qi][0] = a.x; q[qi][1] = a.y; q[qi][2] = a.z; q[qi][3] = a.w; q[qi][4] = bq.x; q[qi][5] = bq.y; q[qi][6] = bq.z; q[qi][7] = bq.w;
;             rsq[qi] = (1.0f / sqrtf(ssq[(r0 + qi) * 4 + h] * (1.f / 256.f) + EPS)) * (0.0625f * 1.4426950408889634f); }
.LBB0_3144:
	s_lshl_b32 s12, s34, 3
	s_add_i32 s0, s12, 0x4000
	v_mbcnt_lo_u32_b32 v117, -1, 0
	v_mbcnt_hi_u32_b32 v117, -1, v117
	s_add_i32 s4, s12, 0x4001
	v_ashrrev_i32_e32 v66, 4, v117
	v_lshl_add_u32 v0, s0, 2, v66
	v_ashrrev_i32_e32 v1, 31, v0
	v_lshl_add_u64 v[0:1], v[0:1], 2, s[8:9]
	global_load_dword v28, v[0:1], off
	v_lshl_add_u32 v0, s4, 2, v66
	v_ashrrev_i32_e32 v1, 31, v0
	v_lshl_add_u64 v[0:1], v[0:1], 2, s[8:9]
	s_add_i32 s40, s12, 0x4002
	global_load_dword v29, v[0:1], off
	v_lshl_add_u32 v0, s40, 2, v66
	v_ashrrev_i32_e32 v1, 31, v0
	v_lshl_add_u64 v[0:1], v[0:1], 2, s[8:9]
	global_load_dword v30, v[0:1], off
	v_lshlrev_b32_e32 v64, 4, v117
	v_ashrrev_i32_e32 v65, 31, v64
	s_ashr_i32 s5, s4, 31
	s_waitcnt vmcnt(18)
	v_lshl_add_u64 v[52:53], v[64:65], 1, s[18:19]
	s_lshl_b64 s[4:5], s[4:5], 11
	s_waitcnt vmcnt(10)
	v_lshl_add_u64 v[12:13], v[52:53], 0, s[4:5]
	s_add_i32 s4, s12, 0x4003
	s_add_i32 s38, s12, 0x4004
	s_ashr_i32 s1, s0, 31
	s_ashr_i32 s5, s4, 31
	v_lshl_add_u32 v4, s4, 2, v66
	s_waitcnt vmcnt(3)
	v_lshl_add_u32 v6, s38, 2, v66
	s_lshl_b64 s[36:37], s[0:1], 11
	s_lshl_b64 s[0:1], s[4:5], 11
	v_ashrrev_i32_e32 v5, 31, v4
	v_ashrrev_i32_e32 v7, 31, v6
	v_lshl_add_u64 v[8:9], v[52:53], 0, s[36:37]
	v_lshl_add_u64 v[20:21], v[52:53], 0, s[0:1]
	global_load_dwordx4 v[0:3], v[12:13], off offset:16
	v_lshl_add_u64 v[24:25], v[4:5], 2, s[8:9]
	v_lshl_add_u64 v[26:27], v[6:7], 2, s[8:9]
	global_load_dwordx4 v[4:7], v[8:9], off
	s_nop 0
	global_load_dwordx4 v[8:11], v[8:9], off offset:16
	s_nop 0
	global_load_dwordx4 v[12:15], v[12:13], off
	s_nop 0
	global_load_dwordx4 v[16:19], v[20:21], off
	s_nop 0
	global_load_dwordx4 v[20:23], v[20:21], off offset:16
	s_nop 0
	global_load_dword v32, v[24:25], off
	s_ashr_i32 s41, s40, 31
	s_ashr_i32 s39, s38, 31
	v_lshl_add_u32 v126, v66, 10, s3
	v_lshl_add_u64 v[112:113], v[64:65], 2, s[22:23]
	s_waitcnt vmcnt(9)
	v_fmamk_f32 v24, v28, 0x3b800000, v114
	v_cmp_gt_f32_e32 vcc, s47, v24
	s_waitcnt vmcnt(8)
	v_fmamk_f32 v25, v29, 0x3b800000, v114
	v_mul_f32_e32 v29, 0x4f800000, v24
	v_cndmask_b32_e32 v24, v24, v29, vcc
	v_cmp_gt_f32_e64 s[0:1], s47, v25
	s_waitcnt vmcnt(7)
	v_fmamk_f32 v28, v30, 0x3b800000, v114
	v_mul_f32_e32 v30, 0x4f800000, v25
	v_cndmask_b32_e64 v25, v25, v30, s[0:1]
	v_sqrt_f32_e32 v29, v24
	v_sqrt_f32_e32 v30, v25
	v_mul_f32_e32 v31, 0x4f800000, v28
	v_cmp_gt_f32_e64 s[4:5], s47, v28
	v_add_u32_e32 v33, -1, v29
	v_add_u32_e32 v35, -1, v30
	v_fma_f32 v37, -v33, v29, v24
	v_add_u32_e32 v34, 1, v29
	v_fma_f32 v39, -v35, v30, v25
	v_cmp_ge_f32_e64 s[6:7], 0, v37
	v_add_u32_e32 v36, 1, v30
	v_fma_f32 v38, -v34, v29, v24
	v_cndmask_b32_e64 v29, v29, v33, s[6:7]
	v_cmp_ge_f32_e64 s[6:7], 0, v39
	v_fma_f32 v40, -v36, v30, v25
	v_cndmask_b32_e64 v28, v28, v31, s[4:5]
	v_cndmask_b32_e64 v30, v30, v35, s[6:7]
	v_cmp_lt_f32_e64 s[6:7], 0, v38
	v_sqrt_f32_e32 v31, v28
	s_waitcnt vmcnt(0)
	v_fmamk_f32 v32, v32, 0x3b800000, v114
	v_cndmask_b32_e64 v29, v29, v34, s[6:7]
	v_cmp_lt_f32_e64 s[6:7], 0, v40
	v_mul_f32_e32 v33, 0x37800000, v29
	v_cndmask_b32_e32 v29, v29, v33, vcc
	v_cndmask_b32_e64 v30, v30, v36, s[6:7]
	v_mul_f32_e32 v34, 0x37800000, v30
	v_cmp_class_f32_e32 vcc, v24, v115
	v_cndmask_b32_e64 v30, v30, v34, s[0:1]
	s_nop 0
	v_cndmask_b32_e32 v24, v29, v24, vcc
	v_cmp_class_f32_e32 vcc, v25, v115
	v_div_scale_f32 v29, s[0:1], v24, v24, 1.0
	s_nop 0
	v_cndmask_b32_e32 v25, v30, v25, vcc
	v_div_scale_f32 v33, s[0:1], v25, v25, 1.0
	v_rcp_f32_e32 v35, v33
	v_div_scale_f32 v36, s[0:1], 1.0, v25, 1.0
	v_rcp_f32_e32 v34, v29
	v_fma_f32 v38, -v33, v35, 1.0
	v_fmac_f32_e32 v35, v38, v35
	v_mul_f32_e32 v38, v36, v35
	v_fma_f32 v40, -v33, v38, v36
	v_fmac_f32_e32 v38, v40, v35
	global_load_dword v40, v[26:27], off
	v_fma_f32 v37, -v29, v34, 1.0
	v_div_scale_f32 v30, vcc, 1.0, v24, 1.0
	v_fmac_f32_e32 v34, v37, v34
	v_mul_f32_e32 v37, v30, v34
	v_fma_f32 v39, -v29, v37, v30
	v_fmac_f32_e32 v37, v39, v34
	v_fma_f32 v29, -v29, v37, v30
	v_fma_f32 v30, -v33, v38, v36
	v_div_fmas_f32 v29, v29, v34, v37
	s_mov_b64 vcc, s[0:1]
	v_div_fixup_f32 v24, v29, v24, 1.0
	v_div_fmas_f32 v29, v30, v35, v38
	v_mul_f32_e32 v118, 0x3db8aa3b, v24
	v_div_fixup_f32 v24, v29, v25, 1.0
	v_mul_f32_e32 v119, 0x3db8aa3b, v24
	v_add_u32_e32 v24, -1, v31
	v_fma_f32 v25, -v24, v31, v28
	v_cmp_ge_f32_e32 vcc, 0, v25
	v_add_u32_e32 v25, 1, v31
	v_fma_f32 v26, -v25, v31, v28
	v_cndmask_b32_e32 v24, v31, v24, vcc
	v_cmp_lt_f32_e32 vcc, 0, v26
	s_lshl_b64 s[0:1], s[40:41], 11
	s_waitcnt vmcnt(0)
; __device__ __forceinline__ void memattn_unit(const Ctx& C, int r0, const float* kp0, const float* vp0, unsigned char* lds, int lane) {
;     ...
;         for (int qi = 0; qi < 8; ++qi) { const u32x4 a = *(const u32x4*)(qmem + (size_t)(r0 + qi) * 1024 + lane * 16), bq = *(const u32x4*)(qmem + (size_t)(r0 + qi) * 1024 + lane * 16 + 8);
;             q[qi][0] = a.x; q[qi][1] = a.y; q[qi][2] = a.z; q[qi][3] = a.w; q[qi][4] = bq.x; q[qi][5] = bq.y; q[qi][6] = bq.z; q[qi][7] = bq.w;
;             rsq[qi] = (1.0f / sqrtf(ssq[(r0 + qi) * 4 + h] * (1.f / 256.f) + EPS)) * (0.0625f * 1.4426950408889634f); }
	v_fmamk_f32 v40, v40, 0x3b800000, v114
	v_cndmask_b32_e32 v24, v24, v25, vcc
	v_mul_f32_e32 v25, 0x37800000, v24
	v_cndmask_b32_e64 v24, v24, v25, s[4:5]
	v_cmp_class_f32_e32 vcc, v28, v115
	s_nop 1
	v_cndmask_b32_e32 v41, v24, v28, vcc
	v_div_scale_f32 v42, s[4:5], v41, v41, 1.0
	v_rcp_f32_e32 v43, v42
	s_add_i32 s4, s12, 0x4005
	v_lshl_add_u64 v[28:29], v[52:53], 0, s[0:1]
	v_cmp_gt_f32_e64 s[0:1], s47, v32
	v_fma_f32 v33, -v42, v43, 1.0
	v_fmac_f32_e32 v43, v33, v43
	v_mul_f32_e32 v33, 0x4f800000, v32
	s_ashr_i32 s5, s4, 31
	v_cndmask_b32_e64 v46, v32, v33, s[0:1]
	s_lshl_b64 s[6:7], s[4:5], 11
	v_lshl_add_u32 v32, s4, 2, v66
	v_lshl_add_u64 v[36:37], v[52:53], 0, s[6:7]
	v_ashrrev_i32_e32 v33, 31, v32
	global_load_dwordx4 v[24:27], v[28:29], off
	s_nop 0
	global_load_dwordx4 v[28:31], v[28:29], off offset:16
	v_lshl_add_u64 v[38:39], v[32:33], 2, s[8:9]
	global_load_dwordx4 v[32:35], v[36:37], off offset:16
	global_load_dword v54, v[38:39], off
	v_sqrt_f32_e32 v47, v46
	v_div_scale_f32 v44, vcc, 1.0, v41, 1.0
	v_mul_f32_e32 v45, v44, v43
	v_fma_f32 v38, -v42, v45, v44
	v_fmac_f32_e32 v45, v38, v43
	v_add_u32_e32 v39, -1, v47
	v_fma_f32 v38, -v42, v45, v44
	v_fma_f32 v42, -v39, v47, v46
	v_cmp_ge_f32_e64 s[4:5], 0, v42
	v_add_u32_e32 v42, 1, v47
	v_fma_f32 v44, -v42, v47, v46
	v_cndmask_b32_e64 v39, v47, v39, s[4:5]
	v_cmp_lt_f32_e64 s[4:5], 0, v44
	v_div_fmas_f32 v38, v38, v43, v45
	v_div_fixup_f32 v38, v38, v41, 1.0
	v_cndmask_b32_e64 v39, v39, v42, s[4:5]
	v_mul_f32_e32 v42, 0x37800000, v39
	v_cndmask_b32_e64 v39, v39, v42, s[0:1]
	v_cmp_class_f32_e64 s[0:1], v46, v115
	v_mul_f32_e32 v120, 0x3db8aa3b, v38
	s_add_i32 s6, s12, 0x4006
	v_cndmask_b32_e64 v39, v39, v46, s[0:1]
	v_div_scale_f32 v42, s[0:1], v39, v39, 1.0
	v_rcp_f32_e32 v44, v42
	s_lshl_b64 s[4:5], s[38:39], 11
	v_lshl_add_u64 v[48:49], v[52:53], 0, s[4:5]
	s_ashr_i32 s7, s6, 31
	v_fma_f32 v38, -v42, v44, 1.0
	v_fmac_f32_e32 v44, v38, v44
	v_div_scale_f32 v38, vcc, 1.0, v39, 1.0
	v_mul_f32_e32 v41, v38, v44
	v_fma_f32 v43, -v42, v41, v38
	v_fmac_f32_e32 v41, v43, v44
	v_fma_f32 v38, -v42, v41, v38
	v_div_fmas_f32 v38, v38, v44, v41
	v_div_fixup_f32 v41, v38, v39, 1.0
	v_lshl_add_u32 v38, s6, 2, v66
	v_ashrrev_i32_e32 v39, 31, v38
	v_mul_f32_e32 v42, 0x4f800000, v40
	v_cmp_gt_f32_e32 vcc, s47, v40
	v_lshl_add_u64 v[38:39], v[38:39], 2, s[8:9]
	global_load_dword v67, v[38:39], off
	s_nop 0
	global_load_dwordx4 v[36:39], v[36:37], off
	v_cndmask_b32_e32 v40, v40, v42, vcc
	v_sqrt_f32_e32 v42, v40
	v_mul_f32_e32 v121, 0x3db8aa3b, v41
	v_add_u32_e32 v41, -1, v42
	v_fma_f32 v43, -v41, v42, v40
	v_cmp_ge_f32_e64 s[0:1], 0, v43
	v_add_u32_e32 v43, 1, v42
	s_waitcnt vmcnt(2)
	v_fmamk_f32 v54, v54, 0x3b800000, v114
	v_cndmask_b32_e64 v41, v42, v41, s[0:1]
	v_fma_f32 v42, -v43, v42, v40
	v_cmp_lt_f32_e64 s[0:1], 0, v42
	v_mul_f32_e32 v62, 0x4f800000, v54
	s_waitcnt vmcnt(1)
	v_fmamk_f32 v67, v67, 0x3b800000, v114
	v_cndmask_b32_e64 v41, v41, v43, s[0:1]
	v_mul_f32_e32 v42, 0x37800000, v41
	v_cndmask_b32_e32 v41, v41, v42, vcc
	v_cmp_class_f32_e32 vcc, v40, v115
	v_mul_f32_e32 v74, 0x4f800000, v67
	s_nop 0
	v_cndmask_b32_e32 v55, v41, v40, vcc
	v_div_scale_f32 v56, s[0:1], v55, v55, 1.0
	s_add_i32 s0, s12, 0x4007
	s_ashr_i32 s1, s0, 31
	s_lshl_b64 s[38:39], s[0:1], 11
	v_lshl_add_u32 v40, s0, 2, v66
	v_lshl_add_u64 v[60:61], v[52:53], 0, s[38:39]
	v_ashrrev_i32_e32 v41, 31, v40
	v_lshl_add_u64 v[44:45], v[40:41], 2, s[8:9]
	global_load_dwordx4 v[40:43], v[60:61], off offset:16
	global_load_dword v68, v[44:45], off
	v_rcp_f32_e32 v57, v56
	v_cmp_gt_f32_e64 s[0:1], s47, v54
	global_load_dwordx4 v[44:47], v[48:49], off
	s_nop 0
	global_load_dwordx4 v[48:51], v[48:49], off offset:16
	v_cndmask_b32_e64 v54, v54, v62, s[0:1]
	v_fma_f32 v58, -v56, v57, 1.0
	v_fmac_f32_e32 v57, v58, v57
	v_div_scale_f32 v58, vcc, 1.0, v55, 1.0
	v_sqrt_f32_e32 v62, v54
	v_mul_f32_e32 v59, v58, v57
	v_fma_f32 v63, -v56, v59, v58
	v_fmac_f32_e32 v59, v63, v57
	v_fma_f32 v56, -v56, v59, v58
	v_add_u32_e32 v58, -1, v62
	v_fma_f32 v63, -v58, v62, v54
	v_cmp_ge_f32_e64 s[4:5], 0, v63
	v_add_u32_e32 v63, 1, v62
	s_waitcnt vmcnt(2)
	v_fmamk_f32 v68, v68, 0x3b800000, v114
	v_cndmask_b32_e64 v58, v62, v58, s[4:5]
	v_fma_f32 v62, -v63, v62, v54
	v_cmp_lt_f32_e64 s[4:5], 0, v62
	s_nop 1
	v_cndmask_b32_e64 v58, v58, v63, s[4:5]
	v_mul_f32_e32 v62, 0x37800000, v58
	v_cndmask_b32_e64 v58, v58, v62, s[0:1]
	v_cmp_class_f32_e64 s[0:1], v54, v115
	s_nop 1
	v_cndmask_b32_e64 v69, v58, v54, s[0:1]
	v_div_scale_f32 v70, s[0:1], v69, v69, 1.0
	v_rcp_f32_e32 v71, v70
	v_div_fmas_f32 v54, v56, v57, v59
	v_div_fixup_f32 v54, v54, v55, 1.0
	s_lshl_b64 s[0:1], s[6:7], 11
	v_mul_f32_e32 v122, 0x3db8aa3b, v54
	v_fma_f32 v54, -v70, v71, 1.0
	v_lshl_add_u64 v[56:57], v[52:53], 0, s[0:1]
	v_fmac_f32_e32 v71, v54, v71
	global_load_dwordx4 v[52:55], v[56:57], off
	s_nop 0
	global_load_dwordx4 v[56:59], v[56:57], off offset:16
	s_nop 0
	global_load_dwordx4 v[60:63], v[60:61], off
	v_cmp_gt_f32_e64 s[0:1], s47, v67
	v_div_scale_f32 v72, vcc, 1.0, v69, 1.0
	s_nop 0
	v_cndmask_b32_e64 v67, v67, v74, s[0:1]
	v_sqrt_f32_e32 v74, v67
	v_mul_f32_e32 v73, v72, v71
	v_fma_f32 v75, -v70, v73, v72
	v_fmac_f32_e32 v73, v75, v71
	v_fma_f32 v70, -v70, v73, v72
	v_add_u32_e32 v72, -1, v74
	v_fma_f32 v75, -v72, v74, v67
	v_cmp_ge_f32_e64 s[4:5], 0, v75
	v_add_u32_e32 v75, 1, v74
	v_div_fmas_f32 v70, v70, v71, v73
	v_cndmask_b32_e64 v72, v74, v72, s[4:5]
	v_fma_f32 v74, -v75, v74, v67
	v_cmp_lt_f32_e64 s[4:5], 0, v74
	v_div_fixup_f32 v69, v70, v69, 1.0
	v_mul_f32_e32 v71, 0x4f800000, v68
	v_cndmask_b32_e64 v72, v72, v75, s[4:5]
	v_mul_f32_e32 v74, 0x37800000, v72
; __device__ __forceinline__ unsigned cvt_pk_bf16(float lo, float hi) { unsigned r; asm volatile("v_cvt_pk_bf16_f32 %0, %1, %2" : "=v"(r) : "v"(lo), "v"(hi)); return r; }
; __device__ __forceinline__ float dot2bf(unsigned a, unsigned b, float c) { return __builtin_amdgcn_fdot2_f32_bf16(__builtin_bit_cast(bf16x2_t, a), __builtin_bit_cast(bf16x2_t, b), c, false); }
; __device__ __forceinline__ void memattn_unit(const Ctx& C, int r0, const float* kp0, const float* vp0, unsigned char* lds, int lane) {
;     ...
;         for (int qi = 0; qi < 8; ++qi) { const u32x4 a = *(const u32x4*)(qmem + (size_t)(r0 + qi) * 1024 + lane * 16), bq = *(const u32x4*)(qmem + (size_t)(r0 + qi) * 1024 + lane * 16 + 8);
;             q[qi][0] = a.x; q[qi][1] = a.y; q[qi][2] = a.z; q[qi][3] = a.w; q[qi][4] = bq.x; q[qi][5] = bq.y; q[qi][6] = bq.z; q[qi][7] = bq.w;
;             rsq[qi] = (1.0f / sqrtf(ssq[(r0 + qi) * 4 + h] * (1.f / 256.f) + EPS)) * (0.0625f * 1.4426950408889634f); }
;         const float* kbase = kp0 + (size_t)(32 * w) * 1024 + lane * 16;
; #pragma unroll 1
;         for (int mb = 0; mb < 8; ++mb) {
;             f32x4 kr[4][4];
; #pragma unroll
;             for (int u = 0; u < 4; ++u)
; #pragma unroll
;                 for (int j = 0; j < 4; ++j) kr[u][j] = *(const f32x4*)(kbase + (size_t)(mb * 4 + u) * 1024 + 4 * j);
; #pragma unroll
;             for (int u = 0; u < 4; ++u) {
;                 unsigned kb[8];
; #pragma unroll
;                 for (int j = 0; j < 4; ++j) { kb[2 * j] = cvt_pk_bf16(kr[u][j].x, kr[u][j].y); kb[2 * j + 1] = cvt_pk_bf16(kr[u][j].z, kr[u][j].w); }
;                 const int m = 32 * w + mb * 4 + u;
; #pragma unroll
;                 for (int qi = 0; qi < 8; ++qi) {
;                     float p = 0.f;
; #pragma unroll
;                     for (int e = 0; e < 8; ++e) p = dot2bf(q[qi][e], kb[e], p);
	v_cndmask_b32_e64 v72, v72, v74, s[0:1]
	v_cmp_class_f32_e64 s[0:1], v67, v115
	v_mul_f32_e32 v123, 0x3db8aa3b, v69
	s_nop 0
	v_cndmask_b32_e64 v67, v72, v67, s[0:1]
	v_div_scale_f32 v72, s[0:1], v67, v67, 1.0
	v_rcp_f32_e32 v74, v72
	v_cmp_gt_f32_e64 s[0:1], s47, v68
	v_fma_f32 v69, -v72, v74, 1.0
	s_nop 0
	v_cndmask_b32_e64 v68, v68, v71, s[0:1]
	v_fmac_f32_e32 v74, v69, v74
	v_div_scale_f32 v69, vcc, 1.0, v67, 1.0
	v_sqrt_f32_e32 v71, v68
	v_mul_f32_e32 v70, v69, v74
	v_fma_f32 v73, -v72, v70, v69
	v_fmac_f32_e32 v70, v73, v74
	v_fma_f32 v69, -v72, v70, v69
	v_add_u32_e32 v72, -1, v71
	v_fma_f32 v73, -v72, v71, v68
	v_cmp_ge_f32_e64 s[4:5], 0, v73
	v_add_u32_e32 v73, 1, v71
	v_div_fmas_f32 v69, v69, v74, v70
	v_cndmask_b32_e64 v72, v71, v72, s[4:5]
	v_fma_f32 v71, -v73, v71, v68
	v_cmp_lt_f32_e64 s[4:5], 0, v71
	v_div_fixup_f32 v67, v69, v67, 1.0
	v_mul_f32_e32 v124, 0x3db8aa3b, v67
	v_cndmask_b32_e64 v71, v72, v73, s[4:5]
	v_mul_f32_e32 v72, 0x37800000, v71
	v_cndmask_b32_e64 v71, v71, v72, s[0:1]
	v_cmp_class_f32_e64 s[0:1], v68, v115
	s_mov_b64 s[4:5], 0
	s_nop 0
	v_cndmask_b32_e64 v68, v71, v68, s[0:1]
	v_div_scale_f32 v71, s[0:1], v68, v68, 1.0
	v_rcp_f32_e32 v72, v71
	s_nop 0
	v_fma_f32 v67, -v71, v72, 1.0
	v_fmac_f32_e32 v72, v67, v72
	v_div_scale_f32 v67, vcc, 1.0, v68, 1.0
	v_mul_f32_e32 v69, v67, v72
	v_fma_f32 v70, -v71, v69, v67
	v_fmac_f32_e32 v69, v70, v72
	v_fma_f32 v67, -v71, v69, v67
	v_div_fmas_f32 v67, v67, v72, v69
	v_div_fixup_f32 v67, v67, v68, 1.0
	v_mul_f32_e32 v125, 0x3db8aa3b, v67
	v_and_b32_e32 v67, 15, v117
	v_cmp_eq_u32_e32 vcc, 0, v67
	v_lshl_add_u64 v[236:237], v[112:113], 0, s[4:5]
	v_lshl_add_u64 v[238:239], v[236:237], 0, s[26:27]
	v_lshl_add_u64 v[240:241], v[236:237], 0, s[28:29]
	v_lshl_add_u64 v[242:243], v[236:237], 0, s[30:31]
	global_load_dwordx4 v[148:151], v[236:237], off
	global_load_dwordx4 v[152:155], v[236:237], off offset:16
	global_load_dwordx4 v[156:159], v[236:237], off offset:32
	global_load_dwordx4 v[160:163], v[236:237], off offset:48
	global_load_dwordx4 v[164:167], v[238:239], off
	global_load_dwordx4 v[168:171], v[238:239], off offset:16
	global_load_dwordx4 v[172:175], v[238:239], off offset:32
	global_load_dwordx4 v[176:179], v[238:239], off offset:48
	global_load_dwordx4 v[180:183], v[240:241], off
	global_load_dwordx4 v[184:187], v[240:241], off offset:16
	global_load_dwordx4 v[188:191], v[240:241], off offset:32
	global_load_dwordx4 v[192:195], v[240:241], off offset:48
	global_load_dwordx4 v[196:199], v[242:243], off
	global_load_dwordx4 v[200:203], v[242:243], off offset:16
	global_load_dwordx4 v[204:207], v[242:243], off offset:32
	global_load_dwordx4 v[208:211], v[242:243], off offset:48
.Lmq_loop:
	s_add_u32 s98, s4, 0x4000
	s_min_u32 s98, s98, 0x1c000
	s_mov_b32 s99, 0
	v_lshl_add_u64 v[236:237], v[112:113], 0, s[98:99]
	v_lshl_add_u64 v[238:239], v[236:237], 0, s[26:27]
	v_lshl_add_u64 v[240:241], v[236:237], 0, s[28:29]
	v_lshl_add_u64 v[242:243], v[236:237], 0, s[30:31]
	s_waitcnt vmcnt(12)
	v_cvt_pk_bf16_f32 v212, v148, v149
	v_cvt_pk_bf16_f32 v213, v150, v151
	v_cvt_pk_bf16_f32 v214, v152, v153
	v_cvt_pk_bf16_f32 v215, v154, v155
	v_cvt_pk_bf16_f32 v216, v156, v157
	v_cvt_pk_bf16_f32 v217, v158, v159
	v_cvt_pk_bf16_f32 v218, v160, v161
	v_cvt_pk_bf16_f32 v219, v162, v163
	global_load_dwordx4 v[148:151], v[236:237], off
	global_load_dwordx4 v[152:155], v[236:237], off offset:16
	global_load_dwordx4 v[156:159], v[236:237], off offset:32
	global_load_dwordx4 v[160:163], v[236:237], off offset:48
	v_mov_b32_e32 v220, 0
	v_mov_b32_e32 v221, 0
	v_mov_b32_e32 v222, 0
	v_mov_b32_e32 v223, 0
	v_mov_b32_e32 v224, 0
	v_mov_b32_e32 v225, 0
	v_mov_b32_e32 v226, 0
	v_mov_b32_e32 v227, 0
	v_dot2c_f32_bf16_e32 v220, v4, v212
	v_dot2c_f32_bf16_e32 v221, v12, v212
	v_dot2c_f32_bf16_e32 v222, v24, v212
	v_dot2c_f32_bf16_e32 v223, v16, v212
	v_dot2c_f32_bf16_e32 v224, v44, v212
	v_dot2c_f32_bf16_e32 v225, v36, v212
	v_dot2c_f32_bf16_e32 v226, v52, v212
	v_dot2c_f32_bf16_e32 v227, v60, v212
	v_dot2c_f32_bf16_e32 v220, v5, v213
	v_dot2c_f32_bf16_e32 v221, v13, v213
	v_dot2c_f32_bf16_e32 v222, v25, v213
	v_dot2c_f32_bf16_e32 v223, v17, v213
	v_dot2c_f32_bf16_e32 v224, v45, v213
	v_dot2c_f32_bf16_e32 v225, v37, v213
	v_dot2c_f32_bf16_e32 v226, v53, v213
	v_dot2c_f32_bf16_e32 v227, v61, v213
	v_dot2c_f32_bf16_e32 v220, v6, v214
	v_dot2c_f32_bf16_e32 v221, v14, v214
	v_dot2c_f32_bf16_e32 v222, v26, v214
	v_dot2c_f32_bf16_e32 v223, v18, v214
	v_dot2c_f32_bf16_e32 v224, v46, v214
	v_dot2c_f32_bf16_e32 v225, v38, v214
	v_dot2c_f32_bf16_e32 v226, v54, v214
	v_dot2c_f32_bf16_e32 v227, v62, v214
	v_dot2c_f32_bf16_e32 v220, v7, v215
	v_dot2c_f32_bf16_e32 v221, v15, v215
	v_dot2c_f32_bf16_e32 v222, v27, v215
	v_dot2c_f32_bf16_e32 v223, v19, v215
	v_dot2c_f32_bf16_e32 v224, v47, v215
	v_dot2c_f32_bf16_e32 v225, v39, v215
	v_dot2c_f32_bf16_e32 v226, v55, v215
	v_dot2c_f32_bf16_e32 v227, v63, v215
	v_dot2c_f32_bf16_e32 v220, v8, v216
	v_dot2c_f32_bf16_e32 v221, v0, v216
	v_dot2c_f32_bf16_e32 v222, v28, v216
	v_dot2c_f32_bf16_e32 v223, v20, v216
	v_dot2c_f32_bf16_e32 v224, v48, v216
	v_dot2c_f32_bf16_e32 v225, v32, v216
	v_dot2c_f32_bf16_e32 v226, v56, v216
	v_dot2c_f32_bf16_e32 v227, v40, v216
	v_dot2c_f32_bf16_e32 v220, v9, v217
	v_dot2c_f32_bf16_e32 v221, v1, v217
	v_dot2c_f32_bf16_e32 v222, v29, v217
	v_dot2c_f32_bf16_e32 v223, v21, v217
	v_dot2c_f32_bf16_e32 v224, v49, v217
	v_dot2c_f32_bf16_e32 v225, v33, v217
	v_dot2c_f32_bf16_e32 v226, v57, v217
	v_dot2c_f32_bf16_e32 v227, v41, v217
	v_dot2c_f32_bf16_e32 v220, v10, v218
	v_dot2c_f32_bf16_e32 v221, v2, v218
	v_dot2c_f32_bf16_e32 v222, v30, v218
; __device__ __forceinline__ unsigned cvt_pk_bf16(float lo, float hi) { unsigned r; asm volatile("v_cvt_pk_bf16_f32 %0, %1, %2" : "=v"(r) : "v"(lo), "v"(hi)); return r; }
; __device__ __forceinline__ float dot2bf(unsigned a, unsigned b, float c) { return __builtin_amdgcn_fdot2_f32_bf16(__builtin_bit_cast(bf16x2_t, a), __builtin_bit_cast(bf16x2_t, b), c, false); }
; __device__ __forceinline__ void memattn_unit(const Ctx& C, int r0, const float* kp0, const float* vp0, unsigned char* lds, int lane) {
;     ...
;             for (int u = 0; u < 4; ++u) {
;                 unsigned kb[8];
; #pragma unroll
;                 for (int j = 0; j < 4; ++j) { kb[2 * j] = cvt_pk_bf16(kr[u][j].x, kr[u][j].y); kb[2 * j + 1] = cvt_pk_bf16(kr[u][j].z, kr[u][j].w); }
;                 const int m = 32 * w + mb * 4 + u;
; #pragma unroll
;                 for (int qi = 0; qi < 8; ++qi) {
;                     float p = 0.f;
; #pragma unroll
;                     for (int e = 0; e < 8; ++e) p = dot2bf(q[qi][e], kb[e], p);
;                     p = dpp_sum16(p);
;                     if ((lane & 15) == 0) logits[(qi * 4 + h) * 256 + m] = p * rsq[qi];
	v_dot2c_f32_bf16_e32 v223, v22, v218
	v_dot2c_f32_bf16_e32 v224, v50, v218
	v_dot2c_f32_bf16_e32 v225, v34, v218
	v_dot2c_f32_bf16_e32 v226, v58, v218
	v_dot2c_f32_bf16_e32 v227, v42, v218
	v_dot2c_f32_bf16_e32 v220, v11, v219
	v_dot2c_f32_bf16_e32 v221, v3, v219
	v_dot2c_f32_bf16_e32 v222, v31, v219
	v_dot2c_f32_bf16_e32 v223, v23, v219
	v_dot2c_f32_bf16_e32 v224, v51, v219
	v_dot2c_f32_bf16_e32 v225, v35, v219
	v_dot2c_f32_bf16_e32 v226, v59, v219
	v_dot2c_f32_bf16_e32 v227, v43, v219
	v_add_f32_dpp v220, v220, v220 quad_perm:[1,0,3,2] row_mask:0xf bank_mask:0xf bound_ctrl:1
	v_add_f32_dpp v221, v221, v221 quad_perm:[1,0,3,2] row_mask:0xf bank_mask:0xf bound_ctrl:1
	v_add_f32_dpp v222, v222, v222 quad_perm:[1,0,3,2] row_mask:0xf bank_mask:0xf bound_ctrl:1
	v_add_f32_dpp v223, v223, v223 quad_perm:[1,0,3,2] row_mask:0xf bank_mask:0xf bound_ctrl:1
	v_add_f32_dpp v224, v224, v224 quad_perm:[1,0,3,2] row_mask:0xf bank_mask:0xf bound_ctrl:1
	v_add_f32_dpp v225, v225, v225 quad_perm:[1,0,3,2] row_mask:0xf bank_mask:0xf bound_ctrl:1
	v_add_f32_dpp v226, v226, v226 quad_perm:[1,0,3,2] row_mask:0xf bank_mask:0xf bound_ctrl:1
	v_add_f32_dpp v227, v227, v227 quad_perm:[1,0,3,2] row_mask:0xf bank_mask:0xf bound_ctrl:1
	v_add_f32_dpp v220, v220, v220 quad_perm:[2,3,0,1] row_mask:0xf bank_mask:0xf bound_ctrl:1
	v_add_f32_dpp v221, v221, v221 quad_perm:[2,3,0,1] row_mask:0xf bank_mask:0xf bound_ctrl:1
	v_add_f32_dpp v222, v222, v222 quad_perm:[2,3,0,1] row_mask:0xf bank_mask:0xf bound_ctrl:1
	v_add_f32_dpp v223, v223, v223 quad_perm:[2,3,0,1] row_mask:0xf bank_mask:0xf bound_ctrl:1
	v_add_f32_dpp v224, v224, v224 quad_perm:[2,3,0,1] row_mask:0xf bank_mask:0xf bound_ctrl:1
	v_add_f32_dpp v225, v225, v225 quad_perm:[2,3,0,1] row_mask:0xf bank_mask:0xf bound_ctrl:1
	v_add_f32_dpp v226, v226, v226 quad_perm:[2,3,0,1] row_mask:0xf bank_mask:0xf bound_ctrl:1
	v_add_f32_dpp v227, v227, v227 quad_perm:[2,3,0,1] row_mask:0xf bank_mask:0xf bound_ctrl:1
	v_add_f32_dpp v220, v220, v220 row_half_mirror row_mask:0xf bank_mask:0xf bound_ctrl:1
	v_add_f32_dpp v221, v221, v221 row_half_mirror row_mask:0xf bank_mask:0xf bound_ctrl:1
	v_add_f32_dpp v222, v222, v222 row_half_mirror row_mask:0xf bank_mask:0xf bound_ctrl:1
	v_add_f32_dpp v223, v223, v223 row_half_mirror row_mask:0xf bank_mask:0xf bound_ctrl:1
	v_add_f32_dpp v224, v224, v224 row_half_mirror row_mask:0xf bank_mask:0xf bound_ctrl:1
	v_add_f32_dpp v225, v225, v225 row_half_mirror row_mask:0xf bank_mask:0xf bound_ctrl:1
	v_add_f32_dpp v226, v226, v226 row_half_mirror row_mask:0xf bank_mask:0xf bound_ctrl:1
	v_add_f32_dpp v227, v227, v227 row_half_mirror row_mask:0xf bank_mask:0xf bound_ctrl:1
	v_mov_b32_dpp v228, v220 row_mirror row_mask:0xf bank_mask:0xf bound_ctrl:1
	v_mov_b32_dpp v229, v221 row_mirror row_mask:0xf bank_mask:0xf bound_ctrl:1
	v_mov_b32_dpp v230, v222 row_mirror row_mask:0xf bank_mask:0xf bound_ctrl:1
	v_mov_b32_dpp v231, v223 row_mirror row_mask:0xf bank_mask:0xf bound_ctrl:1
	v_mov_b32_dpp v232, v224 row_mirror row_mask:0xf bank_mask:0xf bound_ctrl:1
	v_mov_b32_dpp v233, v225 row_mirror row_mask:0xf bank_mask:0xf bound_ctrl:1
	v_mov_b32_dpp v234, v226 row_mirror row_mask:0xf bank_mask:0xf bound_ctrl:1
	v_mov_b32_dpp v235, v227 row_mirror row_mask:0xf bank_mask:0xf bound_ctrl:1
	v_add_f32_e32 v220, v220, v228
	v_add_f32_e32 v221, v221, v229
	v_add_f32_e32 v222, v222, v230
	v_add_f32_e32 v223, v223, v231
	v_add_f32_e32 v224, v224, v232
	v_add_f32_e32 v225, v225, v233
	v_add_f32_e32 v226, v226, v234
	v_add_f32_e32 v227, v227, v235
	v_mul_f32_e32 v220, v118, v220
	v_mul_f32_e32 v221, v119, v221
	v_mul_f32_e32 v222, v120, v222
	v_mul_f32_e32 v223, v121, v223
	v_mul_f32_e32 v224, v122, v224
	v_mul_f32_e32 v225, v123, v225
	v_mul_f32_e32 v226, v124, v226
	v_mul_f32_e32 v227, v125, v227
	s_and_saveexec_b64 s[0:1], vcc
	ds_write_b32 v126, v220
	ds_write_b32 v126, v221 offset:4096
	ds_write_b32 v126, v222 offset:8192
	ds_write_b32 v126, v223 offset:12288
	ds_write_b32 v126, v224 offset:16384
	ds_write_b32 v126, v225 offset:20480
	ds_write_b32 v126, v226 offset:24576
	ds_write_b32 v126, v227 offset:28672
	s_or_b64 exec, exec, s[0:1]
	s_waitcnt vmcnt(12)
	v_cvt_pk_bf16_f32 v212, v164, v165
	v_cvt_pk_bf16_f32 v213, v166, v167
	v_cvt_pk_bf16_f32 v214, v168, v169
	v_cvt_pk_bf16_f32 v215, v170, v171
	v_cvt_pk_bf16_f32 v216, v172, v173
	v_cvt_pk_bf16_f32 v217, v174, v175
	v_cvt_pk_bf16_f32 v218, v176, v177
	v_cvt_pk_bf16_f32 v219, v178, v179
	global_load_dwordx4 v[164:167], v[238:239], off
	global_load_dwordx4 v[168:171], v[238:239], off offset:16
	global_load_dwordx4 v[172:175], v[238:239], off offset:32
	global_load_dwordx4 v[176:179], v[238:239], off offset:48
	v_mov_b32_e32 v220, 0
	v_mov_b32_e32 v221, 0
	v_mov_b32_e32 v222, 0
	v_mov_b32_e32 v223, 0
	v_mov_b32_e32 v224, 0
	v_mov_b32_e32 v225, 0
	v_mov_b32_e32 v226, 0
	v_mov_b32_e32 v227, 0
	v_dot2c_f32_bf16_e32 v220, v4, v212
	v_dot2c_f32_bf16_e32 v221, v12, v212
	v_dot2c_f32_bf16_e32 v222, v24, v212
	v_dot2c_f32_bf16_e32 v223, v16, v212
	v_dot2c_f32_bf16_e32 v224, v44, v212
	v_dot2c_f32_bf16_e32 v225, v36, v212
	v_dot2c_f32_bf16_e32 v226, v52, v212
	v_dot2c_f32_bf16_e32 v227, v60, v212
	v_dot2c_f32_bf16_e32 v220, v5, v213
	v_dot2c_f32_bf16_e32 v221, v13, v213
	v_dot2c_f32_bf16_e32 v222, v25, v213
	v_dot2c_f32_bf16_e32 v223, v17, v213
	v_dot2c_f32_bf16_e32 v224, v45, v213
	v_dot2c_f32_bf16_e32 v225, v37, v213
	v_dot2c_f32_bf16_e32 v226, v53, v213
	v_dot2c_f32_bf16_e32 v227, v61, v213
	v_dot2c_f32_bf16_e32 v220, v6, v214
	v_dot2c_f32_bf16_e32 v221, v14, v214
	v_dot2c_f32_bf16_e32 v222, v26, v214
	v_dot2c_f32_bf16_e32 v223, v18, v214
; __device__ __forceinline__ unsigned cvt_pk_bf16(float lo, float hi) { unsigned r; asm volatile("v_cvt_pk_bf16_f32 %0, %1, %2" : "=v"(r) : "v"(lo), "v"(hi)); return r; }
; __device__ __forceinline__ float dot2bf(unsigned a, unsigned b, float c) { return __builtin_amdgcn_fdot2_f32_bf16(__builtin_bit_cast(bf16x2_t, a), __builtin_bit_cast(bf16x2_t, b), c, false); }
; __device__ __forceinline__ void memattn_unit(const Ctx& C, int r0, const float* kp0, const float* vp0, unsigned char* lds, int lane) {
;     ...
;             for (int u = 0; u < 4; ++u) {
;                 unsigned kb[8];
; #pragma unroll
;                 for (int j = 0; j < 4; ++j) { kb[2 * j] = cvt_pk_bf16(kr[u][j].x, kr[u][j].y); kb[2 * j + 1] = cvt_pk_bf16(kr[u][j].z, kr[u][j].w); }
;                 const int m = 32 * w + mb * 4 + u;
; #pragma unroll
;                 for (int qi = 0; qi < 8; ++qi) {
;                     float p = 0.f;
; #pragma unroll
;                     for (int e = 0; e < 8; ++e) p = dot2bf(q[qi][e], kb[e], p);
;                     p = dpp_sum16(p);
;                     if ((lane & 15) == 0) logits[(qi * 4 + h) * 256 + m] = p * rsq[qi];
	v_dot2c_f32_bf16_e32 v224, v46, v214
	v_dot2c_f32_bf16_e32 v225, v38, v214
	v_dot2c_f32_bf16_e32 v226, v54, v214
	v_dot2c_f32_bf16_e32 v227, v62, v214
	v_dot2c_f32_bf16_e32 v220, v7, v215
	v_dot2c_f32_bf16_e32 v221, v15, v215
	v_dot2c_f32_bf16_e32 v222, v27, v215
	v_dot2c_f32_bf16_e32 v223, v19, v215
	v_dot2c_f32_bf16_e32 v224, v47, v215
	v_dot2c_f32_bf16_e32 v225, v39, v215
	v_dot2c_f32_bf16_e32 v226, v55, v215
	v_dot2c_f32_bf16_e32 v227, v63, v215
	v_dot2c_f32_bf16_e32 v220, v8, v216
	v_dot2c_f32_bf16_e32 v221, v0, v216
	v_dot2c_f32_bf16_e32 v222, v28, v216
	v_dot2c_f32_bf16_e32 v223, v20, v216
	v_dot2c_f32_bf16_e32 v224, v48, v216
	v_dot2c_f32_bf16_e32 v225, v32, v216
	v_dot2c_f32_bf16_e32 v226, v56, v216
	v_dot2c_f32_bf16_e32 v227, v40, v216
	v_dot2c_f32_bf16_e32 v220, v9, v217
	v_dot2c_f32_bf16_e32 v221, v1, v217
	v_dot2c_f32_bf16_e32 v222, v29, v217
	v_dot2c_f32_bf16_e32 v223, v21, v217
	v_dot2c_f32_bf16_e32 v224, v49, v217
	v_dot2c_f32_bf16_e32 v225, v33, v217
	v_dot2c_f32_bf16_e32 v226, v57, v217
	v_dot2c_f32_bf16_e32 v227, v41, v217
	v_dot2c_f32_bf16_e32 v220, v10, v218
	v_dot2c_f32_bf16_e32 v221, v2, v218
	v_dot2c_f32_bf16_e32 v222, v30, v218
	v_dot2c_f32_bf16_e32 v223, v22, v218
	v_dot2c_f32_bf16_e32 v224, v50, v218
	v_dot2c_f32_bf16_e32 v225, v34, v218
	v_dot2c_f32_bf16_e32 v226, v58, v218
	v_dot2c_f32_bf16_e32 v227, v42, v218
	v_dot2c_f32_bf16_e32 v220, v11, v219
	v_dot2c_f32_bf16_e32 v221, v3, v219
	v_dot2c_f32_bf16_e32 v222, v31, v219
	v_dot2c_f32_bf16_e32 v223, v23, v219
	v_dot2c_f32_bf16_e32 v224, v51, v219
	v_dot2c_f32_bf16_e32 v225, v35, v219
	v_dot2c_f32_bf16_e32 v226, v59, v219
	v_dot2c_f32_bf16_e32 v227, v43, v219
	v_add_f32_dpp v220, v220, v220 quad_perm:[1,0,3,2] row_mask:0xf bank_mask:0xf bound_ctrl:1
	v_add_f32_dpp v221, v221, v221 quad_perm:[1,0,3,2] row_mask:0xf bank_mask:0xf bound_ctrl:1
	v_add_f32_dpp v222, v222, v222 quad_perm:[1,0,3,2] row_mask:0xf bank_mask:0xf bound_ctrl:1
	v_add_f32_dpp v223, v223, v223 quad_perm:[1,0,3,2] row_mask:0xf bank_mask:0xf bound_ctrl:1
	v_add_f32_dpp v224, v224, v224 quad_perm:[1,0,3,2] row_mask:0xf bank_mask:0xf bound_ctrl:1
	v_add_f32_dpp v225, v225, v225 quad_perm:[1,0,3,2] row_mask:0xf bank_mask:0xf bound_ctrl:1
	v_add_f32_dpp v226, v226, v226 quad_perm:[1,0,3,2] row_mask:0xf bank_mask:0xf bound_ctrl:1
	v_add_f32_dpp v227, v227, v227 quad_perm:[1,0,3,2] row_mask:0xf bank_mask:0xf bound_ctrl:1
	v_add_f32_dpp v220, v220, v220 quad_perm:[2,3,0,1] row_mask:0xf bank_mask:0xf bound_ctrl:1
	v_add_f32_dpp v221, v221, v221 quad_perm:[2,3,0,1] row_mask:0xf bank_mask:0xf bound_ctrl:1
	v_add_f32_dpp v222, v222, v222 quad_perm:[2,3,0,1] row_mask:0xf bank_mask:0xf bound_ctrl:1
	v_add_f32_dpp v223, v223, v223 quad_perm:[2,3,0,1] row_mask:0xf bank_mask:0xf bound_ctrl:1
	v_add_f32_dpp v224, v224, v224 quad_perm:[2,3,0,1] row_mask:0xf bank_mask:0xf bound_ctrl:1
	v_add_f32_dpp v225, v225, v225 quad_perm:[2,3,0,1] row_mask:0xf bank_mask:0xf bound_ctrl:1
	v_add_f32_dpp v226, v226, v226 quad_perm:[2,3,0,1] row_mask:0xf bank_mask:0xf bound_ctrl:1
	v_add_f32_dpp v227, v227, v227 quad_perm:[2,3,0,1] row_mask:0xf bank_mask:0xf bound_ctrl:1
	v_add_f32_dpp v220, v220, v220 row_half_mirror row_mask:0xf bank_mask:0xf bound_ctrl:1
	v_add_f32_dpp v221, v221, v221 row_half_mirror row_mask:0xf bank_mask:0xf bound_ctrl:1
	v_add_f32_dpp v222, v222, v222 row_half_mirror row_mask:0xf bank_mask:0xf bound_ctrl:1
	v_add_f32_dpp v223, v223, v223 row_half_mirror row_mask:0xf bank_mask:0xf bound_ctrl:1
	v_add_f32_dpp v224, v224, v224 row_half_mirror row_mask:0xf bank_mask:0xf bound_ctrl:1
	v_add_f32_dpp v225, v225, v225 row_half_mirror row_mask:0xf bank_mask:0xf bound_ctrl:1
	v_add_f32_dpp v226, v226, v226 row_half_mirror row_mask:0xf bank_mask:0xf bound_ctrl:1
	v_add_f32_dpp v227, v227, v227 row_half_mirror row_mask:0xf bank_mask:0xf bound_ctrl:1
	v_mov_b32_dpp v228, v220 row_mirror row_mask:0xf bank_mask:0xf bound_ctrl:1
	v_mov_b32_dpp v229, v221 row_mirror row_mask:0xf bank_mask:0xf bound_ctrl:1
	v_mov_b32_dpp v230, v222 row_mirror row_mask:0xf bank_mask:0xf bound_ctrl:1
	v_mov_b32_dpp v231, v223 row_mirror row_mask:0xf bank_mask:0xf bound_ctrl:1
	v_mov_b32_dpp v232, v224 row_mirror row_mask:0xf bank_mask:0xf bound_ctrl:1
	v_mov_b32_dpp v233, v225 row_mirror row_mask:0xf bank_mask:0xf bound_ctrl:1
	v_mov_b32_dpp v234, v226 row_mirror row_mask:0xf bank_mask:0xf bound_ctrl:1
	v_mov_b32_dpp v235, v227 row_mirror row_mask:0xf bank_mask:0xf bound_ctrl:1
	v_add_f32_e32 v220, v220, v228
	v_add_f32_e32 v221, v221, v229
	v_add_f32_e32 v222, v222, v230
	v_add_f32_e32 v223, v223, v231
	v_add_f32_e32 v224, v224, v232
	v_add_f32_e32 v225, v225, v233
	v_add_f32_e32 v226, v226, v234
	v_add_f32_e32 v227, v227, v235
	v_mul_f32_e32 v220, v118, v220
	v_mul_f32_e32 v221, v119, v221
	v_mul_f32_e32 v222, v120, v222
	v_mul_f32_e32 v223, v121, v223
	v_mul_f32_e32 v224, v122, v224
	v_mul_f32_e32 v225, v123, v225
	v_mul_f32_e32 v226, v124, v226
	v_mul_f32_e32 v227, v125, v227
	s_and_saveexec_b64 s[0:1], vcc
	ds_write_b32 v126, v220 offset:4
	ds_write_b32 v126, v221 offset:4100
	ds_write_b32 v126, v222 offset:8196
	ds_write_b32 v126, v223 offset:12292
	ds_write_b32 v126, v224 offset:16388
	ds_write_b32 v126, v225 offset:20484
	ds_write_b32 v126, v226 offset:24580
	ds_write_b32 v126, v227 offset:28676
	s_or_b64 exec, exec, s[0:1]
	s_waitcnt vmcnt(12)
; __device__ __forceinline__ unsigned cvt_pk_bf16(float lo, float hi) { unsigned r; asm volatile("v_cvt_pk_bf16_f32 %0, %1, %2" : "=v"(r) : "v"(lo), "v"(hi)); return r; }
; __device__ __forceinline__ float dot2bf(unsigned a, unsigned b, float c) { return __builtin_amdgcn_fdot2_f32_bf16(__builtin_bit_cast(bf16x2_t, a), __builtin_bit_cast(bf16x2_t, b), c, false); }
; __device__ __forceinline__ void memattn_unit(const Ctx& C, int r0, const float* kp0, const float* vp0, unsigned char* lds, int lane) {
;     ...
;             for (int u = 0; u < 4; ++u) {
;                 unsigned kb[8];
; #pragma unroll
;                 for (int j = 0; j < 4; ++j) { kb[2 * j] = cvt_pk_bf16(kr[u][j].x, kr[u][j].y); kb[2 * j + 1] = cvt_pk_bf16(kr[u][j].z, kr[u][j].w); }
;                 const int m = 32 * w + mb * 4 + u;
; #pragma unroll
;                 for (int qi = 0; qi < 8; ++qi) {
;                     float p = 0.f;
; #pragma unroll
;                     for (int e = 0; e < 8; ++e) p = dot2bf(q[qi][e], kb[e], p);
;                     p = dpp_sum16(p);
;                     if ((lane & 15) == 0) logits[(qi * 4 + h) * 256 + m] = p * rsq[qi];
	v_cvt_pk_bf16_f32 v212, v180, v181
	v_cvt_pk_bf16_f32 v213, v182, v183
	v_cvt_pk_bf16_f32 v214, v184, v185
	v_cvt_pk_bf16_f32 v215, v186, v187
	v_cvt_pk_bf16_f32 v216, v188, v189
	v_cvt_pk_bf16_f32 v217, v190, v191
	v_cvt_pk_bf16_f32 v218, v192, v193
	v_cvt_pk_bf16_f32 v219, v194, v195
	global_load_dwordx4 v[180:183], v[240:241], off
	global_load_dwordx4 v[184:187], v[240:241], off offset:16
	global_load_dwordx4 v[188:191], v[240:241], off offset:32
	global_load_dwordx4 v[192:195], v[240:241], off offset:48
	v_mov_b32_e32 v220, 0
	v_mov_b32_e32 v221, 0
	v_mov_b32_e32 v222, 0
	v_mov_b32_e32 v223, 0
	v_mov_b32_e32 v224, 0
	v_mov_b32_e32 v225, 0
	v_mov_b32_e32 v226, 0
	v_mov_b32_e32 v227, 0
	v_dot2c_f32_bf16_e32 v220, v4, v212
	v_dot2c_f32_bf16_e32 v221, v12, v212
	v_dot2c_f32_bf16_e32 v222, v24, v212
	v_dot2c_f32_bf16_e32 v223, v16, v212
	v_dot2c_f32_bf16_e32 v224, v44, v212
	v_dot2c_f32_bf16_e32 v225, v36, v212
	v_dot2c_f32_bf16_e32 v226, v52, v212
	v_dot2c_f32_bf16_e32 v227, v60, v212
	v_dot2c_f32_bf16_e32 v220, v5, v213
	v_dot2c_f32_bf16_e32 v221, v13, v213
	v_dot2c_f32_bf16_e32 v222, v25, v213
	v_dot2c_f32_bf16_e32 v223, v17, v213
	v_dot2c_f32_bf16_e32 v224, v45, v213
	v_dot2c_f32_bf16_e32 v225, v37, v213
	v_dot2c_f32_bf16_e32 v226, v53, v213
	v_dot2c_f32_bf16_e32 v227, v61, v213
	v_dot2c_f32_bf16_e32 v220, v6, v214
	v_dot2c_f32_bf16_e32 v221, v14, v214
	v_dot2c_f32_bf16_e32 v222, v26, v214
	v_dot2c_f32_bf16_e32 v223, v18, v214
	v_dot2c_f32_bf16_e32 v224, v46, v214
	v_dot2c_f32_bf16_e32 v225, v38, v214
	v_dot2c_f32_bf16_e32 v226, v54, v214
	v_dot2c_f32_bf16_e32 v227, v62, v214
	v_dot2c_f32_bf16_e32 v220, v7, v215
	v_dot2c_f32_bf16_e32 v221, v15, v215
	v_dot2c_f32_bf16_e32 v222, v27, v215
	v_dot2c_f32_bf16_e32 v223, v19, v215
	v_dot2c_f32_bf16_e32 v224, v47, v215
	v_dot2c_f32_bf16_e32 v225, v39, v215
	v_dot2c_f32_bf16_e32 v226, v55, v215
	v_dot2c_f32_bf16_e32 v227, v63, v215
	v_dot2c_f32_bf16_e32 v220, v8, v216
	v_dot2c_f32_bf16_e32 v221, v0, v216
	v_dot2c_f32_bf16_e32 v222, v28, v216
	v_dot2c_f32_bf16_e32 v223, v20, v216
	v_dot2c_f32_bf16_e32 v224, v48, v216
	v_dot2c_f32_bf16_e32 v225, v32, v216
	v_dot2c_f32_bf16_e32 v226, v56, v216
	v_dot2c_f32_bf16_e32 v227, v40, v216
	v_dot2c_f32_bf16_e32 v220, v9, v217
	v_dot2c_f32_bf16_e32 v221, v1, v217
	v_dot2c_f32_bf16_e32 v222, v29, v217
	v_dot2c_f32_bf16_e32 v223, v21, v217
	v_dot2c_f32_bf16_e32 v224, v49, v217
	v_dot2c_f32_bf16_e32 v225, v33, v217
	v_dot2c_f32_bf16_e32 v226, v57, v217
	v_dot2c_f32_bf16_e32 v227, v41, v217
	v_dot2c_f32_bf16_e32 v220, v10, v218
	v_dot2c_f32_bf16_e32 v221, v2, v218
	v_dot2c_f32_bf16_e32 v222, v30, v218
	v_dot2c_f32_bf16_e32 v223, v22, v218
	v_dot2c_f32_bf16_e32 v224, v50, v218
	v_dot2c_f32_bf16_e32 v225, v34, v218
	v_dot2c_f32_bf16_e32 v226, v58, v218
	v_dot2c_f32_bf16_e32 v227, v42, v218
	v_dot2c_f32_bf16_e32 v220, v11, v219
	v_dot2c_f32_bf16_e32 v221, v3, v219
	v_dot2c_f32_bf16_e32 v222, v31, v219
	v_dot2c_f32_bf16_e32 v223, v23, v219
	v_dot2c_f32_bf16_e32 v224, v51, v219
	v_dot2c_f32_bf16_e32 v225, v35, v219
	v_dot2c_f32_bf16_e32 v226, v59, v219
	v_dot2c_f32_bf16_e32 v227, v43, v219
	v_add_f32_dpp v220, v220, v220 quad_perm:[1,0,3,2] row_mask:0xf bank_mask:0xf bound_ctrl:1
	v_add_f32_dpp v221, v221, v221 quad_perm:[1,0,3,2] row_mask:0xf bank_mask:0xf bound_ctrl:1
	v_add_f32_dpp v222, v222, v222 quad_perm:[1,0,3,2] row_mask:0xf bank_mask:0xf bound_ctrl:1
	v_add_f32_dpp v223, v223, v223 quad_perm:[1,0,3,2] row_mask:0xf bank_mask:0xf bound_ctrl:1
	v_add_f32_dpp v224, v224, v224 quad_perm:[1,0,3,2] row_mask:0xf bank_mask:0xf bound_ctrl:1
	v_add_f32_dpp v225, v225, v225 quad_perm:[1,0,3,2] row_mask:0xf bank_mask:0xf bound_ctrl:1
	v_add_f32_dpp v226, v226, v226 quad_perm:[1,0,3,2] row_mask:0xf bank_mask:0xf bound_ctrl:1
	v_add_f32_dpp v227, v227, v227 quad_perm:[1,0,3,2] row_mask:0xf bank_mask:0xf bound_ctrl:1
	v_add_f32_dpp v220, v220, v220 quad_perm:[2,3,0,1] row_mask:0xf bank_mask:0xf bound_ctrl:1
	v_add_f32_dpp v221, v221, v221 quad_perm:[2,3,0,1] row_mask:0xf bank_mask:0xf bound_ctrl:1
	v_add_f32_dpp v222, v222, v222 quad_perm:[2,3,0,1] row_mask:0xf bank_mask:0xf bound_ctrl:1
	v_add_f32_dpp v223, v223, v223 quad_perm:[2,3,0,1] row_mask:0xf bank_mask:0xf bound_ctrl:1
	v_add_f32_dpp v224, v224, v224 quad_perm:[2,3,0,1] row_mask:0xf bank_mask:0xf bound_ctrl:1
	v_add_f32_dpp v225, v225, v225 quad_perm:[2,3,0,1] row_mask:0xf bank_mask:0xf bound_ctrl:1
	v_add_f32_dpp v226, v226, v226 quad_perm:[2,3,0,1] row_mask:0xf bank_mask:0xf bound_ctrl:1
	v_add_f32_dpp v227, v227, v227 quad_perm:[2,3,0,1] row_mask:0xf bank_mask:0xf bound_ctrl:1
	v_add_f32_dpp v220, v220, v220 row_half_mirror row_mask:0xf bank_mask:0xf bound_ctrl:1
	v_add_f32_dpp v221, v221, v221 row_half_mirror row_mask:0xf bank_mask:0xf bound_ctrl:1
	v_add_f32_dpp v222, v222, v222 row_half_mirror row_mask:0xf bank_mask:0xf bound_ctrl:1
	v_add_f32_dpp v223, v223, v223 row_half_mirror row_mask:0xf bank_mask:0xf bound_ctrl:1
	v_add_f32_dpp v224, v224, v224 row_half_mirror row_mask:0xf bank_mask:0xf bound_ctrl:1
	v_add_f32_dpp v225, v225, v225 row_half_mirror row_mask:0xf bank_mask:0xf bound_ctrl:1
	v_add_f32_dpp v226, v226, v226 row_half_mirror row_mask:0xf bank_mask:0xf bound_ctrl:1
	v_add_f32_dpp v227, v227, v227 row_half_mirror row_mask:0xf bank_mask:0xf bound_ctrl:1
	v_mov_b32_dpp v228, v220 row_mirror row_mask:0xf bank_mask:0xf bound_ctrl:1
	v_mov_b32_dpp v229, v221 row_mirror row_mask:0xf bank_mask:0xf bound_ctrl:1
	v_mov_b32_dpp v230, v222 row_mirror row_mask:0xf bank_mask:0xf bound_ctrl:1
	v_mov_b32_dpp v231, v223 row_mirror row_mask:0xf bank_mask:0xf bound_ctrl:1
	v_mov_b32_dpp v232, v224 row_mirror row_mask:0xf bank_mask:0xf bound_ctrl:1
	v_mov_b32_dpp v233, v225 row_mirror row_mask:0xf bank_mask:0xf bound_ctrl:1
	v_mov_b32_dpp v234, v226 row_mirror row_mask:0xf bank_mask:0xf bound_ctrl:1
	v_mov_b32_dpp v235, v227 row_mirror row_mask:0xf bank_mask:0xf bound_ctrl:1
	v_add_f32_e32 v220, v220, v228
	v_add_f32_e32 v221, v221, v229
	v_add_f32_e32 v222, v222, v230
	v_add_f32_e32 v223, v223, v231
	v_add_f32_e32 v224, v224, v232
	v_add_f32_e32 v225, v225, v233
	v_add_f32_e32 v226, v226, v234
	v_add_f32_e32 v227, v227, v235
	v_mul_f32_e32 v220, v118, v220
	v_mul_f32_e32 v221, v119, v221
	v_mul_f32_e32 v222, v120, v222
	v_mul_f32_e32 v223, v121, v223
	v_mul_f32_e32 v224, v122, v224
	v_mul_f32_e32 v225, v123, v225
	v_mul_f32_e32 v226, v124, v226
	v_mul_f32_e32 v227, v125, v227
	s_and_saveexec_b64 s[0:1], vcc
	ds_write_b32 v126, v220 offset:8
	ds_write_b32 v126, v221 offset:4104
	ds_write_b32 v126, v222 offset:8200
	ds_write_b32 v126, v223 offset:12296
	ds_write_b32 v126, v224 offset:16392
	ds_write_b32 v126, v225 offset:20488
	ds_write_b32 v126, v226 offset:24584
	ds_write_b32 v126, v227 offset:28680
	s_or_b64 exec, exec, s[0:1]
	s_waitcnt vmcnt(12)
; __device__ __forceinline__ unsigned cvt_pk_bf16(float lo, float hi) { unsigned r; asm volatile("v_cvt_pk_bf16_f32 %0, %1, %2" : "=v"(r) : "v"(lo), "v"(hi)); return r; }
; __device__ __forceinline__ float dot2bf(unsigned a, unsigned b, float c) { return __builtin_amdgcn_fdot2_f32_bf16(__builtin_bit_cast(bf16x2_t, a), __builtin_bit_cast(bf16x2_t, b), c, false); }
; __device__ __forceinline__ void memattn_unit(const Ctx& C, int r0, const float* kp0, const float* vp0, unsigned char* lds, int lane) {
;     ...
;         for (int mb = 0; mb < 8; ++mb) {
;             f32x4 kr[4][4];
; #pragma unroll
;             for (int u = 0; u < 4; ++u)
; #pragma unroll
;                 for (int j = 0; j < 4; ++j) kr[u][j] = *(const f32x4*)(kbase + (size_t)(mb * 4 + u) * 1024 + 4 * j);
; #pragma unroll
;             for (int u = 0; u < 4; ++u) {
;                 unsigned kb[8];
; #pragma unroll
;                 for (int j = 0; j < 4; ++j) { kb[2 * j] = cvt_pk_bf16(kr[u][j].x, kr[u][j].y); kb[2 * j + 1] = cvt_pk_bf16(kr[u][j].z, kr[u][j].w); }
;                 const int m = 32 * w + mb * 4 + u;
; #pragma unroll
;                 for (int qi = 0; qi < 8; ++qi) {
;                     float p = 0.f;
; #pragma unroll
;                     for (int e = 0; e < 8; ++e) p = dot2bf(q[qi][e], kb[e], p);
;                     p = dpp_sum16(p);
;                     if ((lane & 15) == 0) logits[(qi * 4 + h) * 256 + m] = p * rsq[qi];
;                 }
;             }
	v_cvt_pk_bf16_f32 v212, v196, v197
	v_cvt_pk_bf16_f32 v213, v198, v199
	v_cvt_pk_bf16_f32 v214, v200, v201
	v_cvt_pk_bf16_f32 v215, v202, v203
	v_cvt_pk_bf16_f32 v216, v204, v205
	v_cvt_pk_bf16_f32 v217, v206, v207
	v_cvt_pk_bf16_f32 v218, v208, v209
	v_cvt_pk_bf16_f32 v219, v210, v211
	global_load_dwordx4 v[196:199], v[242:243], off
	global_load_dwordx4 v[200:203], v[242:243], off offset:16
	global_load_dwordx4 v[204:207], v[242:243], off offset:32
	global_load_dwordx4 v[208:211], v[242:243], off offset:48
	v_mov_b32_e32 v220, 0
	v_mov_b32_e32 v221, 0
	v_mov_b32_e32 v222, 0
	v_mov_b32_e32 v223, 0
	v_mov_b32_e32 v224, 0
	v_mov_b32_e32 v225, 0
	v_mov_b32_e32 v226, 0
	v_mov_b32_e32 v227, 0
	v_dot2c_f32_bf16_e32 v220, v4, v212
	v_dot2c_f32_bf16_e32 v221, v12, v212
	v_dot2c_f32_bf16_e32 v222, v24, v212
	v_dot2c_f32_bf16_e32 v223, v16, v212
	v_dot2c_f32_bf16_e32 v224, v44, v212
	v_dot2c_f32_bf16_e32 v225, v36, v212
	v_dot2c_f32_bf16_e32 v226, v52, v212
	v_dot2c_f32_bf16_e32 v227, v60, v212
	v_dot2c_f32_bf16_e32 v220, v5, v213
	v_dot2c_f32_bf16_e32 v221, v13, v213
	v_dot2c_f32_bf16_e32 v222, v25, v213
	v_dot2c_f32_bf16_e32 v223, v17, v213
	v_dot2c_f32_bf16_e32 v224, v45, v213
	v_dot2c_f32_bf16_e32 v225, v37, v213
	v_dot2c_f32_bf16_e32 v226, v53, v213
	v_dot2c_f32_bf16_e32 v227, v61, v213
	v_dot2c_f32_bf16_e32 v220, v6, v214
	v_dot2c_f32_bf16_e32 v221, v14, v214
	v_dot2c_f32_bf16_e32 v222, v26, v214
	v_dot2c_f32_bf16_e32 v223, v18, v214
	v_dot2c_f32_bf16_e32 v224, v46, v214
	v_dot2c_f32_bf16_e32 v225, v38, v214
	v_dot2c_f32_bf16_e32 v226, v54, v214
	v_dot2c_f32_bf16_e32 v227, v62, v214
	v_dot2c_f32_bf16_e32 v220, v7, v215
	v_dot2c_f32_bf16_e32 v221, v15, v215
	v_dot2c_f32_bf16_e32 v222, v27, v215
	v_dot2c_f32_bf16_e32 v223, v19, v215
	v_dot2c_f32_bf16_e32 v224, v47, v215
	v_dot2c_f32_bf16_e32 v225, v39, v215
	v_dot2c_f32_bf16_e32 v226, v55, v215
	v_dot2c_f32_bf16_e32 v227, v63, v215
	v_dot2c_f32_bf16_e32 v220, v8, v216
	v_dot2c_f32_bf16_e32 v221, v0, v216
	v_dot2c_f32_bf16_e32 v222, v28, v216
	v_dot2c_f32_bf16_e32 v223, v20, v216
	v_dot2c_f32_bf16_e32 v224, v48, v216
	v_dot2c_f32_bf16_e32 v225, v32, v216
	v_dot2c_f32_bf16_e32 v226, v56, v216
	v_dot2c_f32_bf16_e32 v227, v40, v216
	v_dot2c_f32_bf16_e32 v220, v9, v217
	v_dot2c_f32_bf16_e32 v221, v1, v217
	v_dot2c_f32_bf16_e32 v222, v29, v217
	v_dot2c_f32_bf16_e32 v223, v21, v217
	v_dot2c_f32_bf16_e32 v224, v49, v217
	v_dot2c_f32_bf16_e32 v225, v33, v217
	v_dot2c_f32_bf16_e32 v226, v57, v217
	v_dot2c_f32_bf16_e32 v227, v41, v217
	v_dot2c_f32_bf16_e32 v220, v10, v218
	v_dot2c_f32_bf16_e32 v221, v2, v218
	v_dot2c_f32_bf16_e32 v222, v30, v218
	v_dot2c_f32_bf16_e32 v223, v22, v218
	v_dot2c_f32_bf16_e32 v224, v50, v218
	v_dot2c_f32_bf16_e32 v225, v34, v218
	v_dot2c_f32_bf16_e32 v226, v58, v218
	v_dot2c_f32_bf16_e32 v227, v42, v218
	v_dot2c_f32_bf16_e32 v220, v11, v219
	v_dot2c_f32_bf16_e32 v221, v3, v219
	v_dot2c_f32_bf16_e32 v222, v31, v219
	v_dot2c_f32_bf16_e32 v223, v23, v219
	v_dot2c_f32_bf16_e32 v224, v51, v219
	v_dot2c_f32_bf16_e32 v225, v35, v219
	v_dot2c_f32_bf16_e32 v226, v59, v219
	v_dot2c_f32_bf16_e32 v227, v43, v219
	v_add_f32_dpp v220, v220, v220 quad_perm:[1,0,3,2] row_mask:0xf bank_mask:0xf bound_ctrl:1
	v_add_f32_dpp v221, v221, v221 quad_perm:[1,0,3,2] row_mask:0xf bank_mask:0xf bound_ctrl:1
	v_add_f32_dpp v222, v222, v222 quad_perm:[1,0,3,2] row_mask:0xf bank_mask:0xf bound_ctrl:1
	v_add_f32_dpp v223, v223, v223 quad_perm:[1,0,3,2] row_mask:0xf bank_mask:0xf bound_ctrl:1
	v_add_f32_dpp v224, v224, v224 quad_perm:[1,0,3,2] row_mask:0xf bank_mask:0xf bound_ctrl:1
	v_add_f32_dpp v225, v225, v225 quad_perm:[1,0,3,2] row_mask:0xf bank_mask:0xf bound_ctrl:1
	v_add_f32_dpp v226, v226, v226 quad_perm:[1,0,3,2] row_mask:0xf bank_mask:0xf bound_ctrl:1
	v_add_f32_dpp v227, v227, v227 quad_perm:[1,0,3,2] row_mask:0xf bank_mask:0xf bound_ctrl:1
	v_add_f32_dpp v220, v220, v220 quad_perm:[2,3,0,1] row_mask:0xf bank_mask:0xf bound_ctrl:1
	v_add_f32_dpp v221, v221, v221 quad_perm:[2,3,0,1] row_mask:0xf bank_mask:0xf bound_ctrl:1
	v_add_f32_dpp v222, v222, v222 quad_perm:[2,3,0,1] row_mask:0xf bank_mask:0xf bound_ctrl:1
	v_add_f32_dpp v223, v223, v223 quad_perm:[2,3,0,1] row_mask:0xf bank_mask:0xf bound_ctrl:1
	v_add_f32_dpp v224, v224, v224 quad_perm:[2,3,0,1] row_mask:0xf bank_mask:0xf bound_ctrl:1
	v_add_f32_dpp v225, v225, v225 quad_perm:[2,3,0,1] row_mask:0xf bank_mask:0xf bound_ctrl:1
	v_add_f32_dpp v226, v226, v226 quad_perm:[2,3,0,1] row_mask:0xf bank_mask:0xf bound_ctrl:1
	v_add_f32_dpp v227, v227, v227 quad_perm:[2,3,0,1] row_mask:0xf bank_mask:0xf bound_ctrl:1
	v_add_f32_dpp v220, v220, v220 row_half_mirror row_mask:0xf bank_mask:0xf bound_ctrl:1
	v_add_f32_dpp v221, v221, v221 row_half_mirror row_mask:0xf bank_mask:0xf bound_ctrl:1
	v_add_f32_dpp v222, v222, v222 row_half_mirror row_mask:0xf bank_mask:0xf bound_ctrl:1
	v_add_f32_dpp v223, v223, v223 row_half_mirror row_mask:0xf bank_mask:0xf bound_ctrl:1
	v_add_f32_dpp v224, v224, v224 row_half_mirror row_mask:0xf bank_mask:0xf bound_ctrl:1
	v_add_f32_dpp v225, v225, v225 row_half_mirror row_mask:0xf bank_mask:0xf bound_ctrl:1
	v_add_f32_dpp v226, v226, v226 row_half_mirror row_mask:0xf bank_mask:0xf bound_ctrl:1
	v_add_f32_dpp v227, v227, v227 row_half_mirror row_mask:0xf bank_mask:0xf bound_ctrl:1
	v_mov_b32_dpp v228, v220 row_mirror row_mask:0xf bank_mask:0xf bound_ctrl:1
	v_mov_b32_dpp v229, v221 row_mirror row_mask:0xf bank_mask:0xf bound_ctrl:1
	v_mov_b32_dpp v230, v222 row_mirror row_mask:0xf bank_mask:0xf bound_ctrl:1
	v_mov_b32_dpp v231, v223 row_mirror row_mask:0xf bank_mask:0xf bound_ctrl:1
	v_mov_b32_dpp v232, v224 row_mirror row_mask:0xf bank_mask:0xf bound_ctrl:1
	v_mov_b32_dpp v233, v225 row_mirror row_mask:0xf bank_mask:0xf bound_ctrl:1
	v_mov_b32_dpp v234, v226 row_mirror row_mask:0xf bank_mask:0xf bound_ctrl:1
	v_mov_b32_dpp v235, v227 row_mirror row_mask:0xf bank_mask:0xf bound_ctrl:1
	v_add_f32_e32 v220, v220, v228
	v_add_f32_e32 v221, v221, v229
	v_add_f32_e32 v222, v222, v230
	v_add_f32_e32 v223, v223, v231
	v_add_f32_e32 v224, v224, v232
	v_add_f32_e32 v225, v225, v233
	v_add_f32_e32 v226, v226, v234
	v_add_f32_e32 v227, v227, v235
	v_mul_f32_e32 v220, v118, v220
	v_mul_f32_e32 v221, v119, v221
	v_mul_f32_e32 v222, v120, v222
	v_mul_f32_e32 v223, v121, v223
	v_mul_f32_e32 v224, v122, v224
	v_mul_f32_e32 v225, v123, v225
	v_mul_f32_e32 v226, v124, v226
	v_mul_f32_e32 v227, v125, v227
	s_and_saveexec_b64 s[0:1], vcc
	ds_write_b32 v126, v220 offset:12
	ds_write_b32 v126, v221 offset:4108
	ds_write_b32 v126, v222 offset:8204
	ds_write_b32 v126, v223 offset:12300
	ds_write_b32 v126, v224 offset:16396
	ds_write_b32 v126, v225 offset:20492
	ds_write_b32 v126, v226 offset:24588
	ds_write_b32 v126, v227 offset:28684
	s_or_b64 exec, exec, s[0:1]
	s_add_u32 s4, s4, 0x4000
	s_addc_u32 s5, s5, 0
	v_add_u32_e32 v126, 16, v126
	s_cmp_eq_u32 s4, 0x20000
	s_cbranch_scc0 .Lmq_loop

; __global__ void __launch_bounds__(NTHREADS, 2) fwd(Args args) {
	.amdhsa_kernel _Z3fwd4Args
		.amdhsa_group_segment_fixed_size 0
		.amdhsa_private_segment_fixed_size 0
		.amdhsa_kernarg_size 512
		.amdhsa_user_sgpr_count 2
		.amdhsa_user_sgpr_dispatch_ptr 0
		.amdhsa_user_sgpr_queue_ptr 0
		.amdhsa_user_sgpr_kernarg_segment_ptr 1
		.amdhsa_user_sgpr_dispatch_id 0
		.amdhsa_user_sgpr_kernarg_preload_length 0
		.amdhsa_user_sgpr_kernarg_preload_offset 0
		.amdhsa_user_sgpr_private_segment_size 0
		.amdhsa_uses_dynamic_stack 0
		.amdhsa_enable_private_segment 0
		.amdhsa_system_sgpr_workgroup_id_x 1
		.amdhsa_system_sgpr_workgroup_id_y 0
		.amdhsa_system_sgpr_workgroup_id_z 0
		.amdhsa_system_sgpr_workgroup_info 0
		.amdhsa_system_vgpr_workitem_id 0
		.amdhsa_next_free_vgpr 251
		.amdhsa_next_free_sgpr 102
		.amdhsa_accum_offset 252
		.amdhsa_reserve_vcc 1
		.amdhsa_float_round_mode_32 0
		.amdhsa_float_round_mode_16_64 0
		.amdhsa_float_denorm_mode_32 3
		.amdhsa_float_denorm_mode_16_64 3
		.amdhsa_dx10_clamp 1
		.amdhsa_ieee_mode 1
		.amdhsa_fp16_overflow 0
		.amdhsa_tg_split 0
		.amdhsa_exception_fp_ieee_invalid_op 0
		.amdhsa_exception_fp_denorm_src 0
		.amdhsa_exception_fp_ieee_div_zero 0
		.amdhsa_exception_fp_ieee_overflow 0
		.amdhsa_exception_fp_ieee_underflow 0
		.amdhsa_exception_fp_ieee_inexact 0
		.amdhsa_exception_int_div_zero 0
	.end_amdhsa_kernel
